# v11 + drop thread-0 buffer_inv before the block barrier at 9 grid-sync exits (second invalidate after the barrier kept)
# speedup vs baseline: 1.0080x; 1.0006x over previous
; #define PG8_STAGE(bufoff, gbase, voff) do { _Pragma("unroll") for (int _i = 0; _i < 2; ++_i) \
;         __builtin_amdgcn_global_load_lds((const unsigned*)((const char*)(gbase) + (voff)[_i]), (LAS unsigned*)(lds + (bufoff) + ldsw + _i * 8192), 16, 0, 0); } while (0)
; #define PG8_WAIT_V(n) asm volatile("s_waitcnt vmcnt(" #n ")" ::: "memory")
; #define PG8_BAR __builtin_amdgcn_s_barrier()
; __device__ __forceinline__ void grid_sync(cg::grid_group& grid) {
;     asm volatile("s_waitcnt vmcnt(0) lgkmcnt(0)" ::: "memory"); grid.sync();
;     __builtin_amdgcn_fence(__ATOMIC_ACQUIRE, "agent"); asm volatile("s_waitcnt vmcnt(0)" ::: "memory"); }
; template <class Epi>
; __device__ __forceinline__ void gemm_phase(LAS unsigned char* lds, const Gemm g, const StaticOrder& S, const Epi& E, const int tid) {
;     ...
;     for (int i = 0; i < 2; ++i) { int R, C; stage_rc(tid * 16 + i * 8192, R, C); const int Rb = Epi::PERM ? ((R & ~31) + perm32(R & 31)) : R;
;         voffA[i] = (unsigned)(R * lda + C) * 2u; voffB[i] = (unsigned)(Rb * K + C) * 2u; }
;     const size_t kstep = (size_t)(BK * 2);
;     const size_t hstepA = (size_t)HALF * lda * 2, hstepB = (size_t)HALF * K * 2;
;     const size_t tstepA = 2 * hstepA, tstepB = 2 * hstepB;
;     const unsigned ldsw = (unsigned)wid * 1024u;
;     const int aoff = lds_byte(wr * 64 + fr, fq * 8), boff = lds_byte(wc * 32 + fr, fq * 8);
;     ...
;     Unit cur, nxt; int ui = 0;
;     if (!S.next(0, cur)) return;
;     f32x4 acc[2][2][4][2];
; #pragma unroll
;     for (int a = 0; a < 2; ++a)
; #pragma unroll
;         for (int b = 0; b < 2; ++b)
; #pragma unroll
;             for (int m = 0; m < 4; ++m)
; #pragma unroll
;                 for (int n = 0; n < 2; ++n) acc[a][b][m][n] = (f32x4){0.f, 0.f, 0.f, 0.f};
;     h16x8 At[4][2], B0[2][2], B1[2][2];
;     const char* cA = (const char*)g.A + (size_t)cur.pm * tstepA; const char* cB = (const char*)g.Bt + (size_t)cur.pn * tstepB;
;     PG8_STAGE(PG8_SB(0, 0), cB, voffB); PG8_STAGE(PG8_SB(0, 1), cB + hstepB, voffB); PG8_STAGE(PG8_SA(0, 0), cA, voffA); PG8_STAGE(PG8_SA(0, 1), cA + hstepA, voffA);
;     if (wr == 1) PG8_BAR;
;     PG8_WAIT_V(2); PG8_BAR;
;     PG8_STAGE(PG8_SB(1, 0), cB + kstep, voffB); PG8_STAGE(PG8_SA(1, 0), cA + kstep, voffA); PG8_STAGE(PG8_SB(1, 1), cB + hstepB + kstep, voffB);
;     PG8_WAIT_V(6); PG8_BAR;
.LBB0_170:
.LBB0_171:
	s_or_b64 exec, exec, s[2:3]
	v_readlane_b32 s2, v249, 11
	v_readlane_b32 s3, v249, 12
	s_barrier
	s_nop 0
	v_cndmask_b32_e64 v0, 0, 1, s[2:3]
	s_waitcnt vmcnt(0)
	buffer_inv sc1
	s_waitcnt vmcnt(0)
	v_cmp_ne_u32_e64 s[4:5], 1, v0
	v_mov_b32_e32 v1, v199
	s_andn2_b64 vcc, exec, s[2:3]
	v_writelane_b32 v254, s4, 40
	v_readfirstlane_b32 s2, v1
	s_nop 0
	v_writelane_b32 v254, s5, 41
	s_cbranch_vccnz .LBB0_187
	v_lshlrev_b32_e32 v4, 4, v1
	v_add_u32_e32 v2, 0x2000, v4
	v_ashrrev_i32_e32 v0, 31, v2
	v_lshrrev_b32_e32 v0, 22, v0
	v_add_u32_e32 v0, v2, v0
	v_ashrrev_i32_e32 v0, 10, v0
	v_mul_i32_i24_e32 v3, 0x400, v0
	v_sub_u32_e32 v2, v2, v3
	v_lshrrev_b32_e32 v3, 4, v2
	v_bitop3_b32 v3, v3, v2, 32 bitop3:0x6c
	v_ashrrev_i32_e32 v2, 31, v3
	v_lshrrev_b32_e32 v2, 26, v2
	v_add_u32_e32 v5, v3, v2
	v_lshlrev_b32_e32 v6, 3, v0
	v_ashrrev_i32_e32 v2, 6, v5
	v_and_b32_e32 v6, -16, v6
	v_add_u32_e32 v6, v2, v6
	v_and_b32_e32 v7, 3, v2
	s_mov_b32 s4, 0x1fffe0
	v_lshrrev_b32_e32 v8, 2, v6
	v_lshlrev_b32_e32 v9, 1, v6
	v_and_b32_e32 v5, 0xc0, v5
	v_and_or_b32 v7, v6, s4, v7
	v_and_b32_e32 v8, 4, v8
	v_and_b32_e32 v9, 24, v9
	v_sub_u32_e32 v3, v3, v5
	v_mov_b32_e32 v12, 1
	v_or3_b32 v7, v7, v8, v9
	v_lshlrev_b32_e32 v8, 5, v0
	v_ashrrev_i16_sdwa v3, v12, sext(v3) dst_sel:DWORD dst_unused:UNUSED_PAD src0_sel:DWORD src1_sel:BYTE_0
	v_and_b32_e32 v8, 32, v8
	v_bfe_i32 v3, v3, 0, 16
	v_add_lshl_u32 v5, v8, v3, 1
	v_lshl_add_u32 v144, v7, 11, v5
	v_lshl_add_u32 v146, v6, 11, v5
	v_bfe_i32 v5, v1, 27, 1
	v_lshrrev_b32_e32 v5, 22, v5
	v_add_u32_e32 v5, v4, v5
	v_and_b32_e32 v5, 0xfffffc00, v5
	v_sub_u32_e32 v4, v4, v5
	v_lshrrev_b32_e32 v5, 4, v4
	v_bitop3_b32 v6, v5, v4, 32 bitop3:0x6c
	v_ashrrev_i32_e32 v5, 31, v1
	v_lshrrev_b32_e32 v5, 26, v5
	v_ashrrev_i32_e32 v4, 31, v6
	v_add_u32_e32 v5, v1, v5
	v_lshrrev_b32_e32 v4, 26, v4
	v_ashrrev_i32_e32 v5, 6, v5
	v_add_u32_e32 v7, v6, v4
	v_lshlrev_b32_e32 v8, 3, v5
	v_ashrrev_i32_e32 v4, 6, v7
	v_and_b32_e32 v8, -16, v8
	v_add_u32_e32 v8, v4, v8
	v_and_b32_e32 v9, 3, v4
	v_lshrrev_b32_e32 v10, 2, v8
	v_lshlrev_b32_e32 v11, 1, v8
	v_and_b32_e32 v7, 0xc0, v7
	v_and_or_b32 v9, v8, s4, v9
	v_and_b32_e32 v10, 4, v10
	v_and_b32_e32 v11, 24, v11
	v_sub_u32_e32 v6, v6, v7
	s_ashr_i32 s3, s2, 6
	v_or3_b32 v9, v9, v10, v11
	v_lshlrev_b32_e32 v10, 5, v5
	v_ashrrev_i16_sdwa v6, v12, sext(v6) dst_sel:DWORD dst_unused:UNUSED_PAD src0_sel:DWORD src1_sel:BYTE_0
	s_lshl_b32 s26, s3, 10
	v_and_b32_e32 v10, 32, v10
	v_bfe_i32 v6, v6, 0, 16
	v_add_lshl_u32 v7, v10, v6, 1
	s_add_i32 s27, s26, 0
	v_readlane_b32 s4, v250, 28
	v_lshl_add_u32 v152, v9, 11, v7
	s_add_i32 m0, s27, 0x10000
	v_readlane_b32 s5, v250, 29
	v_lshl_add_u32 v148, v8, 11, v7
	s_add_i32 s28, s27, 0x2000
	s_add_i32 s29, s27, 0x4000
	s_add_i32 s34, s27, 0x6000
	s_ashr_i32 s6, s2, 8
	global_load_lds_dwordx4 v152, s[4:5]
	s_add_i32 m0, s27, 0x12000
	s_nop 0
	global_load_lds_dwordx4 v144, s[4:5]
	v_readlane_b32 s4, v250, 22
	s_add_i32 m0, s27, 0x14000
	v_readlane_b32 s5, v250, 23
	s_nop 4
	global_load_lds_dwordx4 v152, s[4:5]
	s_add_i32 m0, s27, 0x16000
	s_cmp_eq_u32 s6, 1
	global_load_lds_dwordx4 v144, s[4:5]
	v_readlane_b32 s4, v250, 24
	s_mov_b32 m0, s27
	v_readlane_b32 s5, v250, 25
	s_nop 4
	global_load_lds_dwordx4 v148, s[4:5]
	s_mov_b32 m0, s28
	s_nop 0
	global_load_lds_dwordx4 v146, s[4:5]
	v_readlane_b32 s4, v250, 26
	s_mov_b32 m0, s29
	v_readlane_b32 s5, v250, 27
	s_nop 4
	global_load_lds_dwordx4 v148, s[4:5]
	s_mov_b32 m0, s34
	s_nop 0
	global_load_lds_dwordx4 v146, s[4:5]
	s_cselect_b64 s[4:5], -1, 0
	s_cmp_lg_u32 s6, 1
	s_cbranch_scc1 .LBB0_174
	s_barrier

; #define PG8_STAGE(bufoff, gbase, voff) do { _Pragma("unroll") for (int _i = 0; _i < 2; ++_i) \
;         __builtin_amdgcn_global_load_lds((const unsigned*)((const char*)(gbase) + (voff)[_i]), (LAS unsigned*)(lds + (bufoff) + ldsw + _i * 8192), 16, 0, 0); } while (0)
; #define PG8_WAIT_V(n) asm volatile("s_waitcnt vmcnt(" #n ")" ::: "memory")
; #define PG8_BAR __builtin_amdgcn_s_barrier()
; __device__ __forceinline__ void grid_sync(cg::grid_group& grid) {
;     asm volatile("s_waitcnt vmcnt(0) lgkmcnt(0)" ::: "memory"); grid.sync();
;     __builtin_amdgcn_fence(__ATOMIC_ACQUIRE, "agent"); asm volatile("s_waitcnt vmcnt(0)" ::: "memory"); }
; template <class Epi>
; __device__ __forceinline__ void gemm_phase(LAS unsigned char* lds, const Gemm g, const StaticOrder& S, const Epi& E, const int tid) {
;     ...
;     for (int i = 0; i < 2; ++i) { int R, C; stage_rc(tid * 16 + i * 8192, R, C); const int Rb = Epi::PERM ? ((R & ~31) + perm32(R & 31)) : R;
;         voffA[i] = (unsigned)(R * lda + C) * 2u; voffB[i] = (unsigned)(Rb * K + C) * 2u; }
;     const size_t kstep = (size_t)(BK * 2);
;     const size_t hstepA = (size_t)HALF * lda * 2, hstepB = (size_t)HALF * K * 2;
;     const size_t tstepA = 2 * hstepA, tstepB = 2 * hstepB;
;     const unsigned ldsw = (unsigned)wid * 1024u;
;     const int aoff = lds_byte(wr * 64 + fr, fq * 8), boff = lds_byte(wc * 32 + fr, fq * 8);
;     ...
;     Unit cur, nxt; int ui = 0;
;     if (!S.next(0, cur)) return;
;     f32x4 acc[2][2][4][2];
; #pragma unroll
;     for (int a = 0; a < 2; ++a)
; #pragma unroll
;         for (int b = 0; b < 2; ++b)
; #pragma unroll
;             for (int m = 0; m < 4; ++m)
; #pragma unroll
;                 for (int n = 0; n < 2; ++n) acc[a][b][m][n] = (f32x4){0.f, 0.f, 0.f, 0.f};
;     h16x8 At[4][2], B0[2][2], B1[2][2];
;     const char* cA = (const char*)g.A + (size_t)cur.pm * tstepA; const char* cB = (const char*)g.Bt + (size_t)cur.pn * tstepB;
;     PG8_STAGE(PG8_SB(0, 0), cB, voffB); PG8_STAGE(PG8_SB(0, 1), cB + hstepB, voffB); PG8_STAGE(PG8_SA(0, 0), cA, voffA); PG8_STAGE(PG8_SA(0, 1), cA + hstepA, voffA);
;     if (wr == 1) PG8_BAR;
;     PG8_WAIT_V(2); PG8_BAR;
;     PG8_STAGE(PG8_SB(1, 0), cB + kstep, voffB); PG8_STAGE(PG8_SA(1, 0), cA + kstep, voffA); PG8_STAGE(PG8_SB(1, 1), cB + hstepB + kstep, voffB);
;     PG8_WAIT_V(6); PG8_BAR;
.LBB0_246:
.LBB0_247:
	s_or_b64 exec, exec, s[2:3]
	s_barrier
	s_waitcnt vmcnt(0)
	buffer_inv sc1
	s_waitcnt vmcnt(0)
	v_readlane_b32 s2, v249, 21
	v_mov_b32_e32 v1, v199
	v_readlane_b32 s3, v249, 22
	s_andn2_b64 vcc, exec, s[2:3]
	v_readfirstlane_b32 s2, v1
	s_cbranch_vccnz .LBB0_287
	v_lshlrev_b32_e32 v4, 4, v1
	v_add_u32_e32 v2, 0x2000, v4
	v_ashrrev_i32_e32 v0, 31, v2
	v_lshrrev_b32_e32 v0, 22, v0
	v_add_u32_e32 v0, v2, v0
	v_ashrrev_i32_e32 v0, 10, v0
	v_mul_i32_i24_e32 v3, 0x400, v0
	v_sub_u32_e32 v2, v2, v3
	v_lshrrev_b32_e32 v3, 4, v2
	v_bitop3_b32 v3, v3, v2, 32 bitop3:0x6c
	v_ashrrev_i32_e32 v2, 31, v3
	v_lshrrev_b32_e32 v2, 26, v2
	v_add_u32_e32 v5, v3, v2
	v_lshlrev_b32_e32 v6, 3, v0
	v_ashrrev_i32_e32 v2, 6, v5
	v_and_b32_e32 v6, -16, v6
	v_add_u32_e32 v6, v2, v6
	v_and_b32_e32 v7, 3, v2
	s_mov_b32 s4, 0x1fffe0
	v_lshrrev_b32_e32 v8, 2, v6
	v_lshlrev_b32_e32 v9, 1, v6
	v_and_b32_e32 v5, 0xc0, v5
	v_and_or_b32 v7, v6, s4, v7
	v_and_b32_e32 v8, 4, v8
	v_and_b32_e32 v9, 24, v9
	v_sub_u32_e32 v3, v3, v5
	v_mov_b32_e32 v12, 1
	v_or3_b32 v7, v7, v8, v9
	v_lshlrev_b32_e32 v8, 5, v0
	v_ashrrev_i16_sdwa v3, v12, sext(v3) dst_sel:DWORD dst_unused:UNUSED_PAD src0_sel:DWORD src1_sel:BYTE_0
	v_and_b32_e32 v8, 32, v8
	v_bfe_i32 v3, v3, 0, 16
	v_add_lshl_u32 v5, v8, v3, 1
	v_lshl_add_u32 v128, v7, 11, v5
	v_lshl_add_u32 v130, v6, 11, v5
	v_bfe_i32 v5, v1, 27, 1
	v_lshrrev_b32_e32 v5, 22, v5
	v_add_u32_e32 v5, v4, v5
	v_and_b32_e32 v5, 0xfffffc00, v5
	v_sub_u32_e32 v4, v4, v5
	v_lshrrev_b32_e32 v5, 4, v4
	v_bitop3_b32 v6, v5, v4, 32 bitop3:0x6c
	v_ashrrev_i32_e32 v5, 31, v1
	v_lshrrev_b32_e32 v5, 26, v5
	v_ashrrev_i32_e32 v4, 31, v6
	v_add_u32_e32 v5, v1, v5
	v_lshrrev_b32_e32 v4, 26, v4
	v_ashrrev_i32_e32 v5, 6, v5
	v_add_u32_e32 v7, v6, v4
	v_lshlrev_b32_e32 v8, 3, v5
	v_ashrrev_i32_e32 v4, 6, v7
	v_and_b32_e32 v8, -16, v8
	v_add_u32_e32 v8, v4, v8
	v_and_b32_e32 v9, 3, v4
	v_lshrrev_b32_e32 v10, 2, v8
	v_lshlrev_b32_e32 v11, 1, v8
	v_and_b32_e32 v7, 0xc0, v7
	v_and_or_b32 v9, v8, s4, v9
	v_and_b32_e32 v10, 4, v10
	v_and_b32_e32 v11, 24, v11
	v_sub_u32_e32 v6, v6, v7
	s_ashr_i32 s3, s2, 6
	v_or3_b32 v9, v9, v10, v11
	v_lshlrev_b32_e32 v10, 5, v5
	v_ashrrev_i16_sdwa v6, v12, sext(v6) dst_sel:DWORD dst_unused:UNUSED_PAD src0_sel:DWORD src1_sel:BYTE_0
	s_lshl_b32 s28, s3, 10
	v_and_b32_e32 v10, 32, v10
	v_bfe_i32 v6, v6, 0, 16
	v_add_lshl_u32 v7, v10, v6, 1
	s_add_i32 s29, s28, 0
	v_readlane_b32 s4, v251, 18
	v_lshl_add_u32 v152, v9, 11, v7
	s_add_i32 m0, s29, 0x10000
	v_readlane_b32 s5, v251, 19
	v_lshl_add_u32 v132, v8, 11, v7
	s_add_i32 s34, s29, 0x2000
	s_add_i32 s35, s29, 0x4000
	s_add_i32 s36, s29, 0x6000
	s_ashr_i32 s6, s2, 8
	global_load_lds_dwordx4 v152, s[4:5]
	s_add_i32 m0, s29, 0x12000
	s_nop 0
	global_load_lds_dwordx4 v128, s[4:5]
	v_readlane_b32 s4, v251, 12
	s_add_i32 m0, s29, 0x14000
	v_readlane_b32 s5, v251, 13
	s_nop 4
	global_load_lds_dwordx4 v152, s[4:5]
	s_add_i32 m0, s29, 0x16000
	s_cmp_eq_u32 s6, 1
	global_load_lds_dwordx4 v128, s[4:5]
	v_readlane_b32 s4, v251, 14
	s_mov_b32 m0, s29
	v_readlane_b32 s5, v251, 15
	s_nop 4
	global_load_lds_dwordx4 v132, s[4:5]
	s_mov_b32 m0, s34
	s_nop 0
	global_load_lds_dwordx4 v130, s[4:5]
	v_readlane_b32 s4, v251, 16
	s_mov_b32 m0, s35
	v_readlane_b32 s5, v251, 17
	s_nop 4
	global_load_lds_dwordx4 v132, s[4:5]
	s_mov_b32 m0, s36
	s_nop 0
	global_load_lds_dwordx4 v130, s[4:5]
	s_cselect_b64 s[4:5], -1, 0
	s_cmp_lg_u32 s6, 1
	s_cbranch_scc1 .LBB0_250
	s_barrier

; #define PG8_STAGE(bufoff, gbase, voff) do { _Pragma("unroll") for (int _i = 0; _i < 2; ++_i) \
;         __builtin_amdgcn_global_load_lds((const unsigned*)((const char*)(gbase) + (voff)[_i]), (LAS unsigned*)(lds + (bufoff) + ldsw + _i * 8192), 16, 0, 0); } while (0)
; #define PG8_WAIT_V(n) asm volatile("s_waitcnt vmcnt(" #n ")" ::: "memory")
; #define PG8_BAR __builtin_amdgcn_s_barrier()
; __device__ __forceinline__ void grid_sync(cg::grid_group& grid) {
;     asm volatile("s_waitcnt vmcnt(0) lgkmcnt(0)" ::: "memory"); grid.sync();
;     __builtin_amdgcn_fence(__ATOMIC_ACQUIRE, "agent"); asm volatile("s_waitcnt vmcnt(0)" ::: "memory"); }
; template <class Epi>
; __device__ __forceinline__ void gemm_phase(LAS unsigned char* lds, const Gemm g, const StaticOrder& S, const Epi& E, const int tid) {
;     ...
;     for (int i = 0; i < 2; ++i) { int R, C; stage_rc(tid * 16 + i * 8192, R, C); const int Rb = Epi::PERM ? ((R & ~31) + perm32(R & 31)) : R;
;         voffA[i] = (unsigned)(R * lda + C) * 2u; voffB[i] = (unsigned)(Rb * K + C) * 2u; }
;     const size_t kstep = (size_t)(BK * 2);
;     const size_t hstepA = (size_t)HALF * lda * 2, hstepB = (size_t)HALF * K * 2;
;     const size_t tstepA = 2 * hstepA, tstepB = 2 * hstepB;
;     const unsigned ldsw = (unsigned)wid * 1024u;
;     const int aoff = lds_byte(wr * 64 + fr, fq * 8), boff = lds_byte(wc * 32 + fr, fq * 8);
;     ...
;     Unit cur, nxt; int ui = 0;
;     if (!S.next(0, cur)) return;
;     f32x4 acc[2][2][4][2];
; #pragma unroll
;     for (int a = 0; a < 2; ++a)
; #pragma unroll
;         for (int b = 0; b < 2; ++b)
; #pragma unroll
;             for (int m = 0; m < 4; ++m)
; #pragma unroll
;                 for (int n = 0; n < 2; ++n) acc[a][b][m][n] = (f32x4){0.f, 0.f, 0.f, 0.f};
;     h16x8 At[4][2], B0[2][2], B1[2][2];
;     const char* cA = (const char*)g.A + (size_t)cur.pm * tstepA; const char* cB = (const char*)g.Bt + (size_t)cur.pn * tstepB;
;     PG8_STAGE(PG8_SB(0, 0), cB, voffB); PG8_STAGE(PG8_SB(0, 1), cB + hstepB, voffB); PG8_STAGE(PG8_SA(0, 0), cA, voffA); PG8_STAGE(PG8_SA(0, 1), cA + hstepA, voffA);
;     if (wr == 1) PG8_BAR;
;     PG8_WAIT_V(2); PG8_BAR;
;     PG8_STAGE(PG8_SB(1, 0), cB + kstep, voffB); PG8_STAGE(PG8_SA(1, 0), cA + kstep, voffA); PG8_STAGE(PG8_SB(1, 1), cB + hstepB + kstep, voffB);
;     PG8_WAIT_V(6); PG8_BAR;
.LBB0_296:
.LBB0_297:
	s_or_b64 exec, exec, s[2:3]
	s_barrier
	s_waitcnt vmcnt(0)
	buffer_inv sc1
	s_waitcnt vmcnt(0)
	v_readlane_b32 s4, v249, 23
	v_readlane_b32 s5, v249, 24
	s_mov_b64 s[2:3], -1
	s_and_b64 vcc, exec, s[4:5]
	s_cbranch_vccz .LBB0_624
	v_readlane_b32 s2, v249, 25
	v_readlane_b32 s3, v249, 26
	v_mov_b32_e32 v1, v199
	s_andn2_b64 vcc, exec, s[2:3]
	v_cndmask_b32_e64 v0, 0, 1, s[2:3]
	v_cmp_ne_u32_e64 s[4:5], 1, v0
	v_readfirstlane_b32 s2, v1
	s_nop 0
	v_writelane_b32 v254, s4, 44
	s_nop 1
	v_writelane_b32 v254, s5, 45
	s_cbranch_vccnz .LBB0_314
	v_lshlrev_b32_e32 v4, 4, v1
	v_add_u32_e32 v2, 0x2000, v4
	v_ashrrev_i32_e32 v0, 31, v2
	v_lshrrev_b32_e32 v0, 22, v0
	v_add_u32_e32 v0, v2, v0
	v_ashrrev_i32_e32 v0, 10, v0
	v_mul_i32_i24_e32 v3, 0x400, v0
	v_sub_u32_e32 v2, v2, v3
	v_lshrrev_b32_e32 v3, 4, v2
	v_bitop3_b32 v3, v3, v2, 32 bitop3:0x6c
	v_ashrrev_i32_e32 v2, 31, v3
	v_lshrrev_b32_e32 v2, 26, v2
	v_add_u32_e32 v5, v3, v2
	v_lshlrev_b32_e32 v6, 3, v0
	v_ashrrev_i32_e32 v2, 6, v5
	v_and_b32_e32 v6, -16, v6
	v_add_u32_e32 v6, v2, v6
	v_and_b32_e32 v7, 3, v2
	s_mov_b32 s4, 0x1fffe0
	v_lshrrev_b32_e32 v8, 2, v6
	v_lshlrev_b32_e32 v9, 1, v6
	v_and_b32_e32 v5, 0xc0, v5
	v_and_or_b32 v7, v6, s4, v7
	v_and_b32_e32 v8, 4, v8
	v_and_b32_e32 v9, 24, v9
	v_sub_u32_e32 v3, v3, v5
	v_mov_b32_e32 v12, 1
	v_or3_b32 v7, v7, v8, v9
	v_lshlrev_b32_e32 v8, 5, v0
	v_ashrrev_i16_sdwa v3, v12, sext(v3) dst_sel:DWORD dst_unused:UNUSED_PAD src0_sel:DWORD src1_sel:BYTE_0
	v_and_b32_e32 v8, 32, v8
	v_bfe_i32 v3, v3, 0, 16
	v_add_lshl_u32 v5, v8, v3, 1
	v_lshl_add_u32 v144, v7, 11, v5
	v_lshl_add_u32 v146, v6, 11, v5
	v_bfe_i32 v5, v1, 27, 1
	v_lshrrev_b32_e32 v5, 22, v5
	v_add_u32_e32 v5, v4, v5
	v_and_b32_e32 v5, 0xfffffc00, v5
	v_sub_u32_e32 v4, v4, v5
	v_lshrrev_b32_e32 v5, 4, v4
	v_bitop3_b32 v6, v5, v4, 32 bitop3:0x6c
	v_ashrrev_i32_e32 v5, 31, v1
	v_lshrrev_b32_e32 v5, 26, v5
	v_ashrrev_i32_e32 v4, 31, v6
	v_add_u32_e32 v5, v1, v5
	v_lshrrev_b32_e32 v4, 26, v4
	v_ashrrev_i32_e32 v5, 6, v5
	v_add_u32_e32 v7, v6, v4
	v_lshlrev_b32_e32 v8, 3, v5
	v_ashrrev_i32_e32 v4, 6, v7
	v_and_b32_e32 v8, -16, v8
	v_add_u32_e32 v8, v4, v8
	v_and_b32_e32 v9, 3, v4
	v_lshrrev_b32_e32 v10, 2, v8
	v_lshlrev_b32_e32 v11, 1, v8
	v_and_b32_e32 v7, 0xc0, v7
	v_and_or_b32 v9, v8, s4, v9
	v_and_b32_e32 v10, 4, v10
	v_and_b32_e32 v11, 24, v11
	v_sub_u32_e32 v6, v6, v7
	s_ashr_i32 s3, s2, 6
	v_or3_b32 v9, v9, v10, v11
	v_lshlrev_b32_e32 v10, 5, v5
	v_ashrrev_i16_sdwa v6, v12, sext(v6) dst_sel:DWORD dst_unused:UNUSED_PAD src0_sel:DWORD src1_sel:BYTE_0
	s_lshl_b32 s28, s3, 10
	v_and_b32_e32 v10, 32, v10
	v_bfe_i32 v6, v6, 0, 16
	v_add_lshl_u32 v7, v10, v6, 1
	s_add_i32 s29, s28, 0
	v_readlane_b32 s4, v253, 6
	v_lshl_add_u32 v152, v9, 11, v7
	s_add_i32 m0, s29, 0x10000
	v_readlane_b32 s5, v253, 7
	v_lshl_add_u32 v148, v8, 11, v7
	s_add_i32 s34, s29, 0x2000
	s_add_i32 s35, s29, 0x4000
	s_add_i32 s36, s29, 0x6000
	s_ashr_i32 s6, s2, 8
	global_load_lds_dwordx4 v152, s[4:5]
	s_add_i32 m0, s29, 0x12000
	s_nop 0
	global_load_lds_dwordx4 v144, s[4:5]
	v_readlane_b32 s4, v252, 62
	s_add_i32 m0, s29, 0x14000
	v_readlane_b32 s5, v252, 63
	s_nop 4
	global_load_lds_dwordx4 v152, s[4:5]
	s_add_i32 m0, s29, 0x16000
	s_cmp_eq_u32 s6, 1
	global_load_lds_dwordx4 v144, s[4:5]
	v_readlane_b32 s4, v253, 2
	s_mov_b32 m0, s29
	v_readlane_b32 s5, v253, 3
	s_nop 4
	global_load_lds_dwordx4 v148, s[4:5]
	s_mov_b32 m0, s34
	s_nop 0
	global_load_lds_dwordx4 v146, s[4:5]
	v_readlane_b32 s4, v253, 4
	s_mov_b32 m0, s35
	v_readlane_b32 s5, v253, 5
	s_nop 4
	global_load_lds_dwordx4 v148, s[4:5]
	s_mov_b32 m0, s36
	s_nop 0
	global_load_lds_dwordx4 v146, s[4:5]
	s_cselect_b64 s[4:5], -1, 0
	s_cmp_lg_u32 s6, 1
	s_cbranch_scc1 .LBB0_301
	s_barrier

; __device__ __forceinline__ void grid_sync(cg::grid_group& grid) {
;     asm volatile("s_waitcnt vmcnt(0) lgkmcnt(0)" ::: "memory"); grid.sync();
;     __builtin_amdgcn_fence(__ATOMIC_ACQUIRE, "agent"); asm volatile("s_waitcnt vmcnt(0)" ::: "memory"); }
; __device__ __forceinline__ void st_rwpost(STAGE_ARGS) {
;     ...
;     { const float* gu = args.in[I_GUP] + (size_t)layer * 128 * 512 + (size_t)(8 * (lane >> 4)) * 512 + wave * 64 + (lane & 15);
; #pragma unroll
;       for (int ks = 0; ks < 4; ++ks) {
; #pragma unroll
;           for (int e = 0; e < 8; ++e) { const float g_0 = gu[0], g_1 = gu[16], g_2 = gu[32], g_3 = gu[48]; gu += 512; asm volatile("" : "+v"(gu));
;               bg[0][ks][e] = (h16)g_0; bg[1][ks][e] = (h16)g_1; bg[2][ks][e] = (h16)g_2; bg[3][ks][e] = (h16)g_3; }
;           gu += 24 * 512; asm volatile("" : "+v"(gu)); } }
.LBB0_672:
.LBB0_673:
	s_or_b64 exec, exec, s[2:3]
	s_lshl_b32 s92, s74, 16
	v_mov_b32_e32 v81, v199
	s_lshl_b64 s[4:5], s[92:93], 2
	v_readlane_b32 s8, v248, 32
	s_barrier
	s_waitcnt vmcnt(0)
	buffer_inv sc1
	s_waitcnt vmcnt(0)
	v_readlane_b32 s9, v248, 33
	v_readfirstlane_b32 s2, v81
	v_readlane_b32 s22, v248, 46
	s_add_u32 s4, s8, s4
	v_lshlrev_b32_e32 v0, 10, v81
	v_readlane_b32 s23, v248, 47
	s_addc_u32 s5, s9, s5
	v_and_b32_e32 v152, 0xc000, v0
	s_and_b32 s22, s2, 0xffffffc0
	v_lshl_add_u64 v[0:1], s[4:5], 0, v[152:153]
	s_ashr_i32 s23, s22, 31
	v_and_b32_e32 v64, 15, v81
	v_lshl_add_u64 v[0:1], s[22:23], 2, v[0:1]
	v_lshlrev_b32_e32 v152, 2, v64
	v_lshl_add_u64 v[2:3], v[0:1], 0, v[152:153]
	s_mov_b64 s[4:5], 0x800
	global_load_dword v0, v[2:3], off
	global_load_dword v4, v[2:3], off offset:64
	global_load_dword v8, v[2:3], off offset:128
	global_load_dword v12, v[2:3], off offset:192
	v_lshl_add_u64 v[2:3], v[2:3], 0, s[4:5]
	flat_load_dword v5, v[2:3]
	flat_load_dword v9, v[2:3] offset:64
	flat_load_dword v13, v[2:3] offset:128
	flat_load_dword v16, v[2:3] offset:192
	v_lshl_add_u64 v[2:3], v[2:3], 0, s[4:5]
	flat_load_dword v1, v[2:3]
	flat_load_dword v10, v[2:3] offset:64
	flat_load_dword v14, v[2:3] offset:128
	flat_load_dword v17, v[2:3] offset:192
	v_lshl_add_u64 v[2:3], v[2:3], 0, s[4:5]
	flat_load_dword v6, v[2:3]
	flat_load_dword v11, v[2:3] offset:64
	flat_load_dword v15, v[2:3] offset:128
	flat_load_dword v18, v[2:3] offset:192
	v_lshl_add_u64 v[24:25], v[2:3], 0, s[4:5]
	flat_load_dword v2, v[24:25]
	flat_load_dword v22, v[24:25] offset:64
	flat_load_dword v20, v[24:25] offset:128
	flat_load_dword v19, v[24:25] offset:192
	v_lshl_add_u64 v[24:25], v[24:25], 0, s[4:5]
	flat_load_dword v7, v[24:25]
	flat_load_dword v35, v[24:25] offset:64
	flat_load_dword v23, v[24:25] offset:128
	flat_load_dword v21, v[24:25] offset:192
	v_lshl_add_u64 v[24:25], v[24:25], 0, s[4:5]
	flat_load_dword v3, v[24:25]
	flat_load_dword v42, v[24:25] offset:64
	flat_load_dword v36, v[24:25] offset:128
	flat_load_dword v26, v[24:25] offset:192
	v_lshl_add_u64 v[24:25], v[24:25], 0, s[4:5]
	flat_load_dword v58, v[24:25]
	flat_load_dword v51, v[24:25] offset:64
	flat_load_dword v43, v[24:25] offset:128
	flat_load_dword v37, v[24:25] offset:192
	v_lshl_add_u64 v[24:25], v[24:25], 0, s[4:5]
	s_mov_b64 s[6:7], 0xc000
	v_readlane_b32 s10, v248, 34
	v_lshl_add_u64 v[30:31], v[24:25], 0, s[6:7]
	flat_load_dword v27, v[30:31]
	flat_load_dword v25, v[30:31] offset:64
	flat_load_dword v24, v[30:31] offset:128
	flat_load_dword v28, v[30:31] offset:192
	v_lshl_add_u64 v[40:41], v[30:31], 0, s[4:5]
	flat_load_dword v38, v[40:41]
	flat_load_dword v30, v[40:41] offset:64
	flat_load_dword v29, v[40:41] offset:128
	flat_load_dword v32, v[40:41] offset:192
	v_lshl_add_u64 v[40:41], v[40:41], 0, s[4:5]
	flat_load_dword v46, v[40:41]
	flat_load_dword v39, v[40:41] offset:64
	flat_load_dword v31, v[40:41] offset:128
	flat_load_dword v33, v[40:41] offset:192
	v_lshl_add_u64 v[44:45], v[40:41], 0, s[4:5]
	flat_load_dword v55, v[44:45]
	flat_load_dword v47, v[44:45] offset:64
	flat_load_dword v40, v[44:45] offset:128
	flat_load_dword v34, v[44:45] offset:192
	v_lshl_add_u64 v[44:45], v[44:45], 0, s[4:5]
	flat_load_dword v65, v[44:45]
	flat_load_dword v56, v[44:45] offset:64
	flat_load_dword v49, v[44:45] offset:128
	flat_load_dword v41, v[44:45] offset:192
	v_lshl_add_u64 v[44:45], v[44:45], 0, s[4:5]
	flat_load_dword v74, v[44:45]
	flat_load_dword v66, v[44:45] offset:64
	flat_load_dword v57, v[44:45] offset:128
	flat_load_dword v50, v[44:45] offset:192
	v_lshl_add_u64 v[44:45], v[44:45], 0, s[4:5]
	flat_load_dword v84, v[44:45]
	flat_load_dword v75, v[44:45] offset:64
	flat_load_dword v67, v[44:45] offset:128
	flat_load_dword v59, v[44:45] offset:192
	v_lshl_add_u64 v[44:45], v[44:45], 0, s[4:5]
	flat_load_dword v93, v[44:45]
	flat_load_dword v85, v[44:45] offset:64
	flat_load_dword v76, v[44:45] offset:128
	flat_load_dword v68, v[44:45] offset:192
	v_lshl_add_u64 v[44:45], v[44:45], 0, s[4:5]
	v_readlane_b32 s11, v248, 35
	v_lshl_add_u64 v[62:63], v[44:45], 0, s[6:7]
	flat_load_dword v60, v[62:63]
	flat_load_dword v52, v[62:63] offset:64
	flat_load_dword v45, v[62:63] offset:128
	flat_load_dword v44, v[62:63] offset:192
	v_lshl_add_u64 v[62:63], v[62:63], 0, s[4:5]
	flat_load_dword v70, v[62:63]
	flat_load_dword v61, v[62:63] offset:64
	flat_load_dword v53, v[62:63] offset:128
	flat_load_dword v48, v[62:63] offset:192
	v_lshl_add_u64 v[72:73], v[62:63], 0, s[4:5]
	flat_load_dword v79, v[72:73]
	flat_load_dword v71, v[72:73] offset:64
	flat_load_dword v62, v[72:73] offset:128
	flat_load_dword v54, v[72:73] offset:192
	v_lshl_add_u64 v[82:83], v[72:73], 0, s[4:5]
	flat_load_dword v89, v[82:83]
	flat_load_dword v80, v[82:83] offset:64
	flat_load_dword v72, v[82:83] offset:128
	flat_load_dword v63, v[82:83] offset:192
	v_lshl_add_u64 v[86:87], v[82:83], 0, s[4:5]
	flat_load_dword v98, v[86:87]
	flat_load_dword v90, v[86:87] offset:64
	flat_load_dword v82, v[86:87] offset:128
	flat_load_dword v73, v[86:87] offset:192
	v_lshl_add_u64 v[86:87], v[86:87], 0, s[4:5]
	flat_load_dword v106, v[86:87]
	flat_load_dword v99, v[86:87] offset:64
	flat_load_dword v91, v[86:87] offset:128
	flat_load_dword v83, v[86:87] offset:192
	v_lshl_add_u64 v[86:87], v[86:87], 0, s[4:5]
	flat_load_dword v113, v[86:87]
	flat_load_dword v107, v[86:87] offset:64
	flat_load_dword v100, v[86:87] offset:128
	flat_load_dword v92, v[86:87] offset:192
	v_lshl_add_u64 v[86:87], v[86:87], 0, s[4:5]
	flat_load_dword v119, v[86:87]
	flat_load_dword v114, v[86:87] offset:64
	flat_load_dword v108, v[86:87] offset:128
; __device__ __forceinline__ void st_rwpost(STAGE_ARGS) {
;     ...
;     { const float* gu = args.in[I_GUP] + (size_t)layer * 128 * 512 + (size_t)(8 * (lane >> 4)) * 512 + wave * 64 + (lane & 15);
; #pragma unroll
;       for (int ks = 0; ks < 4; ++ks) {
; #pragma unroll
;           for (int e = 0; e < 8; ++e) { const float g_0 = gu[0], g_1 = gu[16], g_2 = gu[32], g_3 = gu[48]; gu += 512; asm volatile("" : "+v"(gu));
;               bg[0][ks][e] = (h16)g_0; bg[1][ks][e] = (h16)g_1; bg[2][ks][e] = (h16)g_2; bg[3][ks][e] = (h16)g_3; }
;           gu += 24 * 512; asm volatile("" : "+v"(gu)); } }
	flat_load_dword v101, v[86:87] offset:192
	v_lshl_add_u64 v[86:87], v[86:87], 0, s[4:5]
	v_readlane_b32 s12, v248, 36
	v_lshl_add_u64 v[96:97], v[86:87], 0, s[6:7]
	flat_load_dword v94, v[96:97]
	flat_load_dword v86, v[96:97] offset:64
	flat_load_dword v77, v[96:97] offset:128
	flat_load_dword v69, v[96:97] offset:192
	v_lshl_add_u64 v[96:97], v[96:97], 0, s[4:5]
	flat_load_dword v102, v[96:97]
	flat_load_dword v95, v[96:97] offset:64
	flat_load_dword v87, v[96:97] offset:128
	flat_load_dword v78, v[96:97] offset:192
	v_lshl_add_u64 v[104:105], v[96:97], 0, s[4:5]
	flat_load_dword v109, v[104:105]
	flat_load_dword v103, v[104:105] offset:64
	flat_load_dword v96, v[104:105] offset:128
	flat_load_dword v88, v[104:105] offset:192
	v_lshl_add_u64 v[116:117], v[104:105], 0, s[4:5]
	flat_load_dword v115, v[116:117]
	flat_load_dword v110, v[116:117] offset:64
	flat_load_dword v104, v[116:117] offset:128
	flat_load_dword v97, v[116:117] offset:192
	v_lshl_add_u64 v[122:123], v[116:117], 0, s[4:5]
	flat_load_dword v120, v[122:123]
	flat_load_dword v116, v[122:123] offset:64
	flat_load_dword v111, v[122:123] offset:128
	flat_load_dword v105, v[122:123] offset:192
	v_lshl_add_u64 v[122:123], v[122:123], 0, s[4:5]
	flat_load_dword v124, v[122:123]
	flat_load_dword v121, v[122:123] offset:64
	flat_load_dword v117, v[122:123] offset:128
	flat_load_dword v112, v[122:123] offset:192
	v_lshl_add_u64 v[128:129], v[122:123], 0, s[4:5]
	flat_load_dword v127, v[128:129]
	flat_load_dword v125, v[128:129] offset:64
	flat_load_dword v122, v[128:129] offset:128
	flat_load_dword v118, v[128:129] offset:192
	v_lshl_add_u64 v[130:131], v[128:129], 0, s[4:5]
	flat_load_dword v129, v[130:131]
	flat_load_dword v128, v[130:131] offset:64
	flat_load_dword v126, v[130:131] offset:128
	flat_load_dword v123, v[130:131] offset:192
	v_lshl_add_u64 v[130:131], v[130:131], 0, s[4:5]
	v_readlane_b32 s4, v254, 42
	v_readlane_b32 s5, v254, 43
	v_lshl_add_u64 v[130:131], v[130:131], 0, s[6:7]
	s_and_b64 vcc, exec, s[4:5]
	v_readlane_b32 s13, v248, 37
	v_readlane_b32 s14, v248, 38
	v_readlane_b32 s15, v248, 39
	v_readlane_b32 s16, v248, 40
	v_readlane_b32 s17, v248, 41
	v_readlane_b32 s18, v248, 42
	v_readlane_b32 s19, v248, 43
	v_readlane_b32 s20, v248, 44
	v_readlane_b32 s21, v248, 45
	s_cbranch_vccnz .LBB0_728
; #define LAS __attribute__((address_space(3)))
; __device__ __forceinline__ float sigmoidf_(float x) { return __builtin_amdgcn_rcpf(1.0f + __expf(-x)); }
; __device__ __forceinline__ void rwpost_tile(const Args& a, int layer, int tile, LAS unsigned char* lds, int tid, int lane, int wave, const h16x8 (&bg)[4][4]) {
;     ...
;     const float* mu = a.in[I_MU] + l * 1920;
;     LAS h16* G = (LAS h16*)lds;
;     { const int c = tid & 127; const float mug = mu[1536 + 256 + c];
; #pragma unroll 8
;       for (int e = tid; e < 64 * 128; e += NTHREADS) { const int tk = e >> 7; const int m = m0 + tk; const int t = m - tok0s;
;         const float gl = shiftmix(LOWS + (size_t)m * 384 + 256 + c, 384, t, T, mug); G[e] = (h16)sigmoidf_(gl); } }
;     float muv[4], lw[4], lb[4];
; #pragma unroll
;     for (int nt = 0; nt < 4; ++nt) { const int col = wave * 64 + 16 * nt + n16; muv[nt] = mu[1024 + col]; lw[nt] = a.in[I_LNW][l * 512 + col]; lb[nt] = a.in[I_LNB][l * 512 + col]; }
; __device__ __forceinline__ void st_rwpost(STAGE_ARGS) {
;     ...
;           for (int e = 0; e < 8; ++e) { const float g_0 = gu[0], g_1 = gu[16], g_2 = gu[32], g_3 = gu[48]; gu += 512; asm volatile("" : "+v"(gu));
;               bg[0][ks][e] = (h16)g_0; bg[1][ks][e] = (h16)g_1; bg[2][ks][e] = (h16)g_2; bg[3][ks][e] = (h16)g_3; }
	s_mul_i32 s6, s74, 0x1e00
	s_lshl_b64 s[4:5], s[74:75], 9
	v_readlane_b32 s72, v248, 16
	s_ashr_i32 s2, s2, 6
	s_movk_i32 s3, 0x2000
	v_readlane_b32 s73, v248, 17
	v_cmp_gt_i32_e64 s[12:13], s3, v81
	s_ashr_i32 s3, s2, 31
	v_readlane_b32 s74, v248, 18
	v_readlane_b32 s75, v248, 19
	v_readlane_b32 s76, v248, 20
	v_readlane_b32 s77, v248, 21
	v_readlane_b32 s78, v248, 22
	v_readlane_b32 s79, v248, 23
	v_readlane_b32 s80, v248, 24
	v_readlane_b32 s81, v248, 25
	s_mov_b64 s[36:37], s[72:73]
	s_lshl_b64 s[24:25], s[2:3], 3
	s_mov_b64 s[42:43], s[78:79]
	s_waitcnt vmcnt(0) lgkmcnt(0)
	v_cvt_pk_f16_f32 v2, v2, v7
	v_cvt_pk_f16_f32 v7, v42, v51
	v_cvt_pk_f16_f32 v4, v4, v9
	v_cvt_pk_f16_f32 v9, v14, v15
	v_cvt_pk_f16_f32 v15, v26, v37
	v_cvt_pk_f16_f32 v37, v71, v80
	v_cvt_pk_f16_f32 v42, v82, v91
	v_and_b32_e32 v80, 0x7f, v81
	v_or_b32_e32 v82, s22, v64
	s_add_u32 s2, s42, s6
	v_cvt_pk_f16_f32 v8, v8, v13
	v_cvt_pk_f16_f32 v13, v17, v18
	v_cvt_pk_f16_f32 v17, v46, v55
	v_cvt_pk_f16_f32 v46, v73, v83
	v_ashrrev_i32_e32 v83, 31, v82
	v_readlane_b32 s82, v248, 26
	v_readlane_b32 s83, v248, 27
	v_readlane_b32 s84, v248, 28
	v_readlane_b32 s85, v248, 29
	v_readlane_b32 s86, v248, 30
	v_readlane_b32 s87, v248, 31
	s_addc_u32 s3, s43, 0
	v_lshlrev_b32_e32 v152, 2, v80
	v_cvt_pk_f16_f32 v1, v1, v6
	v_cvt_pk_f16_f32 v0, v0, v5
	v_cvt_pk_f16_f32 v6, v22, v35
	v_cvt_pk_f16_f32 v5, v10, v11
	v_cvt_pk_f16_f32 v10, v20, v23
	v_cvt_pk_f16_f32 v12, v12, v16
	v_cvt_pk_f16_f32 v16, v27, v38
	v_cvt_pk_f16_f32 v22, v56, v66
	v_cvt_pk_f16_f32 v20, v25, v30
	v_cvt_pk_f16_f32 v27, v67, v76
	v_cvt_pk_f16_f32 v25, v31, v40
	v_cvt_pk_f16_f32 v31, v59, v68
	v_cvt_pk_f16_f32 v28, v28, v32
	v_cvt_pk_f16_f32 v32, v60, v70
	v_cvt_pk_f16_f32 v60, v69, v78
	v_lshl_add_u64 v[66:67], s[4:5], 0, v[82:83]
	s_mov_b64 s[38:39], s[74:75]
	s_mov_b64 s[40:41], s[76:77]
	s_mov_b64 s[44:45], s[80:81]
	v_readlane_b32 s72, v248, 32
	v_lshl_add_u64 v[68:69], s[2:3], 0, v[152:153]
	s_mov_b64 s[4:5], 0x1c00
	v_cvt_pk_f16_f32 v14, v19, v21
	v_cvt_pk_f16_f32 v19, v84, v93
	v_cvt_pk_f16_f32 v23, v75, v85
	v_readlane_b32 s80, v248, 40
	v_readlane_b32 s81, v248, 41
	v_readlane_b32 s82, v248, 42
	v_readlane_b32 s83, v248, 43
	v_lshl_add_u64 v[84:85], v[68:69], 0, s[4:5]
	v_lshl_add_u64 v[68:69], v[82:83], 2, s[2:3]
	s_mov_b64 s[2:3], 0x1000
	v_lshlrev_b64 v[66:67], 2, v[66:67]
	v_cvt_pk_f16_f32 v11, v36, v43
	v_cvt_pk_f16_f32 v24, v24, v29
	v_cvt_pk_f16_f32 v29, v33, v34
	v_cvt_pk_f16_f32 v33, v79, v89
	v_cvt_pk_f16_f32 v38, v90, v99
	v_cvt_pk_f16_f32 v36, v52, v61
	v_cvt_pk_f16_f32 v52, v86, v95
	v_cvt_pk_f16_f32 v56, v77, v87
	v_cvt_pk_f16_f32 v61, v88, v97
	v_lshl_add_u64 v[86:87], v[68:69], 0, s[2:3]
	v_lshl_add_u64 v[88:89], s[80:81], 0, v[66:67]
	v_lshl_add_u64 v[90:91], s[82:83], 0, v[66:67]
	s_mov_b64 s[2:3], 0x1040
	v_max_i32_e32 v66, 0x1e00, v81
	v_cvt_pk_f16_f32 v21, v39, v47
	v_cvt_pk_f16_f32 v47, v92, v101
	v_lshl_add_u64 v[92:93], v[68:69], 0, s[2:3]
	s_mov_b64 s[2:3], 0x1080
	v_sub_u32_e32 v66, v66, v81
	v_cvt_pk_f16_f32 v44, v44, v48
	v_cvt_pk_f16_f32 v48, v94, v102
	v_lshl_add_u64 v[94:95], v[68:69], 0, s[2:3]
	s_mov_b64 s[2:3], 0x10c0
	v_add_u32_e32 v66, 0x1ff, v66
	v_cvt_pk_f16_f32 v26, v49, v57
	v_cvt_pk_f16_f32 v57, v96, v104
	v_lshl_add_u64 v[96:97], v[68:69], 0, s[2:3]
	v_lshrrev_b32_e32 v67, 9, v66
	v_and_b32_e32 v68, 0xe00, v66
	s_movk_i32 s2, 0xe00
	v_cvt_pk_f16_f32 v18, v65, v74
	v_lshrrev_b32_e32 v65, 2, v81
	v_and_b32_e32 v70, 48, v81
	v_add_u32_e32 v67, 1, v67
	v_cmp_ne_u32_e64 s[14:15], s2, v68
	s_movk_i32 s2, 0xdff
	v_and_b32_e32 v65, 12, v65
	v_and_b32_e32 v67, 7, v67
	v_cmp_lt_u32_e64 s[16:17], s2, v66
	v_lshl_or_b32 v66, v64, 8, v70
	v_readlane_b32 s2, v253, 56
	v_cvt_pk_f16_f32 v3, v3, v58
	v_cvt_pk_f16_f32 v30, v41, v50
	v_cvt_pk_f16_f32 v35, v113, v119
	v_cvt_pk_f16_f32 v34, v98, v106
	v_cvt_pk_f16_f32 v39, v107, v114
	v_cvt_pk_f16_f32 v43, v100, v108
	v_cvt_pk_f16_f32 v41, v62, v72
	v_cvt_pk_f16_f32 v40, v45, v53
	v_cvt_pk_f16_f32 v45, v54, v63
	v_cvt_pk_f16_f32 v51, v127, v129
	v_cvt_pk_f16_f32 v50, v120, v124
	v_cvt_pk_f16_f32 v49, v109, v115
	v_cvt_pk_f16_f32 v55, v125, v128
	v_cvt_pk_f16_f32 v54, v116, v121
	v_cvt_pk_f16_f32 v53, v103, v110
	v_cvt_pk_f16_f32 v59, v122, v126
	v_cvt_pk_f16_f32 v58, v111, v117
	v_cvt_pk_f16_f32 v63, v118, v123
	v_cvt_pk_f16_f32 v62, v105, v112
	s_mov_b32 s45, 0.5
	s_movk_i32 s44, 0x300
	s_movk_i32 s39, 0xfff
	v_readlane_b32 s31, v253, 57
	v_lshl_add_u32 v118, v81, 1, 0
	v_sub_u32_e32 v119, 0, v67
	v_add_u32_e32 v120, 0, v66
	v_add_u32_e32 v121, s2, v65
	v_lshlrev_b32_e32 v152, 1, v64
	s_mov_b32 s35, s68
	v_readlane_b32 s73, v248, 33
	v_readlane_b32 s74, v248, 34
	v_readlane_b32 s75, v248, 35
	v_readlane_b32 s76, v248, 36
	v_readlane_b32 s77, v248, 37
	v_readlane_b32 s78, v248, 38
	v_readlane_b32 s79, v248, 39
	v_readlane_b32 s84, v248, 44
	v_readlane_b32 s85, v248, 45
	v_readlane_b32 s86, v248, 46
	v_readlane_b32 s87, v248, 47

; #define PG8_STAGE(bufoff, gbase, voff) do { _Pragma("unroll") for (int _i = 0; _i < 2; ++_i) \
;         __builtin_amdgcn_global_load_lds((const unsigned*)((const char*)(gbase) + (voff)[_i]), (LAS unsigned*)(lds + (bufoff) + ldsw + _i * 8192), 16, 0, 0); } while (0)
; #define PG8_WAIT_V(n) asm volatile("s_waitcnt vmcnt(" #n ")" ::: "memory")
; #define PG8_BAR __builtin_amdgcn_s_barrier()
; __device__ __forceinline__ void grid_sync(cg::grid_group& grid) {
;     asm volatile("s_waitcnt vmcnt(0) lgkmcnt(0)" ::: "memory"); grid.sync();
;     __builtin_amdgcn_fence(__ATOMIC_ACQUIRE, "agent"); asm volatile("s_waitcnt vmcnt(0)" ::: "memory"); }
; template <class Epi>
; __device__ __forceinline__ void gemm_phase(LAS unsigned char* lds, const Gemm g, const StaticOrder& S, const Epi& E, const int tid) {
;     ...
;     for (int i = 0; i < 2; ++i) { int R, C; stage_rc(tid * 16 + i * 8192, R, C); const int Rb = Epi::PERM ? ((R & ~31) + perm32(R & 31)) : R;
;         voffA[i] = (unsigned)(R * lda + C) * 2u; voffB[i] = (unsigned)(Rb * K + C) * 2u; }
;     const size_t kstep = (size_t)(BK * 2);
;     const size_t hstepA = (size_t)HALF * lda * 2, hstepB = (size_t)HALF * K * 2;
;     const size_t tstepA = 2 * hstepA, tstepB = 2 * hstepB;
;     const unsigned ldsw = (unsigned)wid * 1024u;
;     const int aoff = lds_byte(wr * 64 + fr, fq * 8), boff = lds_byte(wc * 32 + fr, fq * 8);
;     ...
;     Unit cur, nxt; int ui = 0;
;     if (!S.next(0, cur)) return;
;     f32x4 acc[2][2][4][2];
; #pragma unroll
;     for (int a = 0; a < 2; ++a)
; #pragma unroll
;         for (int b = 0; b < 2; ++b)
; #pragma unroll
;             for (int m = 0; m < 4; ++m)
; #pragma unroll
;                 for (int n = 0; n < 2; ++n) acc[a][b][m][n] = (f32x4){0.f, 0.f, 0.f, 0.f};
;     h16x8 At[4][2], B0[2][2], B1[2][2];
;     const char* cA = (const char*)g.A + (size_t)cur.pm * tstepA; const char* cB = (const char*)g.Bt + (size_t)cur.pn * tstepB;
;     PG8_STAGE(PG8_SB(0, 0), cB, voffB); PG8_STAGE(PG8_SB(0, 1), cB + hstepB, voffB); PG8_STAGE(PG8_SA(0, 0), cA, voffA); PG8_STAGE(PG8_SA(0, 1), cA + hstepA, voffA);
;     if (wr == 1) PG8_BAR;
;     PG8_WAIT_V(2); PG8_BAR;
;     PG8_STAGE(PG8_SB(1, 0), cB + kstep, voffB); PG8_STAGE(PG8_SA(1, 0), cA + kstep, voffA); PG8_STAGE(PG8_SB(1, 1), cB + hstepB + kstep, voffB);
;     PG8_WAIT_V(6); PG8_BAR;
.LBB0_780:
.LBB0_781:
	s_or_b64 exec, exec, s[2:3]
	s_barrier
	s_waitcnt vmcnt(0)
	buffer_inv sc1
	s_waitcnt vmcnt(0)
	v_readlane_b32 s2, v254, 42
	v_mov_b32_e32 v1, v199
	v_readlane_b32 s3, v254, 43
	s_and_b64 vcc, exec, s[2:3]
	v_readfirstlane_b32 s2, v1
	s_cbranch_vccnz .LBB0_817
	v_lshlrev_b32_e32 v5, 4, v1
	v_add_u32_e32 v2, 0x2000, v5
	v_ashrrev_i32_e32 v0, 31, v2
	v_lshrrev_b32_e32 v0, 22, v0
	v_add_u32_e32 v0, v2, v0
	v_ashrrev_i32_e32 v0, 10, v0
	v_lshlrev_b32_e32 v3, 5, v0
	v_and_b32_e32 v4, 32, v3
	v_mul_i32_i24_e32 v3, 0x400, v0
	v_sub_u32_e32 v2, v2, v3
	v_lshrrev_b32_e32 v3, 4, v2
	v_bitop3_b32 v3, v3, v2, 32 bitop3:0x6c
	v_ashrrev_i32_e32 v2, 31, v3
	v_lshrrev_b32_e32 v2, 26, v2
	v_add_u32_e32 v6, v3, v2
	v_ashrrev_i32_e32 v2, 6, v6
	v_and_b32_e32 v6, 0xc0, v6
	v_sub_u32_e32 v3, v3, v6
	v_mov_b32_e32 v9, 1
	v_ashrrev_i16_sdwa v3, v9, sext(v3) dst_sel:DWORD dst_unused:UNUSED_PAD src0_sel:DWORD src1_sel:BYTE_0
	v_lshlrev_b32_e32 v6, 3, v0
	v_bfe_i32 v3, v3, 0, 16
	v_and_b32_e32 v6, 0x1ffff0, v6
	v_add_u32_e32 v4, v4, v3
	v_add_lshl_u32 v6, v2, v6, 11
	v_lshl_add_u32 v170, v4, 1, v6
	v_ashrrev_i32_e32 v4, 31, v1
	v_lshrrev_b32_e32 v4, 26, v4
	v_add_u32_e32 v4, v1, v4
	v_ashrrev_i32_e32 v4, 6, v4
	v_lshlrev_b32_e32 v6, 5, v4
	v_and_b32_e32 v7, 32, v6
	v_bfe_i32 v6, v1, 27, 1
	v_lshrrev_b32_e32 v6, 22, v6
	v_add_u32_e32 v6, v5, v6
	v_and_b32_e32 v6, 0xfffffc00, v6
	v_sub_u32_e32 v5, v5, v6
	v_lshrrev_b32_e32 v6, 4, v5
	v_bitop3_b32 v6, v6, v5, 32 bitop3:0x6c
	v_ashrrev_i32_e32 v5, 31, v6
	v_lshrrev_b32_e32 v5, 26, v5
	v_add_u32_e32 v8, v6, v5
	v_ashrrev_i32_e32 v5, 6, v8
	v_and_b32_e32 v8, 0xc0, v8
	v_sub_u32_e32 v6, v6, v8
	s_ashr_i32 s3, s2, 6
	v_ashrrev_i16_sdwa v6, v9, sext(v6) dst_sel:DWORD dst_unused:UNUSED_PAD src0_sel:DWORD src1_sel:BYTE_0
	v_lshlrev_b32_e32 v8, 3, v4
	s_lshl_b32 s28, s3, 10
	v_bfe_i32 v6, v6, 0, 16
	v_and_b32_e32 v8, 0x1ffff0, v8
	v_add_u32_e32 v7, v7, v6
	v_add_lshl_u32 v8, v5, v8, 11
	s_add_i32 s29, s28, 0
	v_readlane_b32 s4, v252, 22
	v_lshl_add_u32 v152, v7, 1, v8
	s_add_i32 m0, s29, 0x10000
	v_readlane_b32 s5, v252, 23
	s_add_i32 s35, s29, 0x2000
	s_add_i32 s36, s29, 0x4000
	s_add_i32 s37, s29, 0x6000
	s_ashr_i32 s6, s2, 8
	s_nop 0
	global_load_lds_dwordx4 v152, s[4:5]
	s_add_i32 m0, s29, 0x12000
	s_nop 0
	global_load_lds_dwordx4 v170, s[4:5]
	v_readlane_b32 s4, v252, 14
	s_add_i32 m0, s29, 0x14000
	v_readlane_b32 s5, v252, 15
	s_nop 4
	global_load_lds_dwordx4 v152, s[4:5]
	s_add_i32 m0, s29, 0x16000
	s_cmp_eq_u32 s6, 1
	global_load_lds_dwordx4 v170, s[4:5]
	v_readlane_b32 s4, v252, 18
	s_mov_b32 m0, s29
	v_readlane_b32 s5, v252, 19
	s_nop 4
	global_load_lds_dwordx4 v152, s[4:5]
	s_mov_b32 m0, s35
	s_nop 0
	global_load_lds_dwordx4 v170, s[4:5]
	v_readlane_b32 s4, v252, 20
	s_mov_b32 m0, s36
	v_readlane_b32 s5, v252, 21
	s_nop 4
	global_load_lds_dwordx4 v152, s[4:5]
	s_mov_b32 m0, s37
	s_nop 0
	global_load_lds_dwordx4 v170, s[4:5]
	s_cselect_b64 s[4:5], -1, 0
	s_cmp_lg_u32 s6, 1
	s_cbranch_scc1 .LBB0_784
	s_barrier

; #define PG8_STAGE(bufoff, gbase, voff) do { _Pragma("unroll") for (int _i = 0; _i < 2; ++_i) \
;         __builtin_amdgcn_global_load_lds((const unsigned*)((const char*)(gbase) + (voff)[_i]), (LAS unsigned*)(lds + (bufoff) + ldsw + _i * 8192), 16, 0, 0); } while (0)
; #define PG8_WAIT_V(n) asm volatile("s_waitcnt vmcnt(" #n ")" ::: "memory")
; #define PG8_BAR __builtin_amdgcn_s_barrier()
; __device__ __forceinline__ void grid_sync(cg::grid_group& grid) {
;     asm volatile("s_waitcnt vmcnt(0) lgkmcnt(0)" ::: "memory"); grid.sync();
;     __builtin_amdgcn_fence(__ATOMIC_ACQUIRE, "agent"); asm volatile("s_waitcnt vmcnt(0)" ::: "memory"); }
; template <class Epi>
; __device__ __forceinline__ void gemm_phase(LAS unsigned char* lds, const Gemm g, const StaticOrder& S, const Epi& E, const int tid) {
;     ...
;     for (int i = 0; i < 2; ++i) { int R, C; stage_rc(tid * 16 + i * 8192, R, C); const int Rb = Epi::PERM ? ((R & ~31) + perm32(R & 31)) : R;
;         voffA[i] = (unsigned)(R * lda + C) * 2u; voffB[i] = (unsigned)(Rb * K + C) * 2u; }
;     const size_t kstep = (size_t)(BK * 2);
;     const size_t hstepA = (size_t)HALF * lda * 2, hstepB = (size_t)HALF * K * 2;
;     const size_t tstepA = 2 * hstepA, tstepB = 2 * hstepB;
;     const unsigned ldsw = (unsigned)wid * 1024u;
;     const int aoff = lds_byte(wr * 64 + fr, fq * 8), boff = lds_byte(wc * 32 + fr, fq * 8);
;     ...
;     Unit cur, nxt; int ui = 0;
;     if (!S.next(0, cur)) return;
;     f32x4 acc[2][2][4][2];
; #pragma unroll
;     for (int a = 0; a < 2; ++a)
; #pragma unroll
;         for (int b = 0; b < 2; ++b)
; #pragma unroll
;             for (int m = 0; m < 4; ++m)
; #pragma unroll
;                 for (int n = 0; n < 2; ++n) acc[a][b][m][n] = (f32x4){0.f, 0.f, 0.f, 0.f};
;     h16x8 At[4][2], B0[2][2], B1[2][2];
;     const char* cA = (const char*)g.A + (size_t)cur.pm * tstepA; const char* cB = (const char*)g.Bt + (size_t)cur.pn * tstepB;
;     PG8_STAGE(PG8_SB(0, 0), cB, voffB); PG8_STAGE(PG8_SB(0, 1), cB + hstepB, voffB); PG8_STAGE(PG8_SA(0, 0), cA, voffA); PG8_STAGE(PG8_SA(0, 1), cA + hstepA, voffA);
;     if (wr == 1) PG8_BAR;
;     PG8_WAIT_V(2); PG8_BAR;
;     PG8_STAGE(PG8_SB(1, 0), cB + kstep, voffB); PG8_STAGE(PG8_SA(1, 0), cA + kstep, voffA); PG8_STAGE(PG8_SB(1, 1), cB + hstepB + kstep, voffB);
;     PG8_WAIT_V(6); PG8_BAR;
.LBB0_852:
.LBB0_853:
	s_or_b64 exec, exec, s[2:3]
	s_barrier
	buffer_inv sc1
	s_waitcnt vmcnt(0)
	v_readlane_b32 s2, v254, 40
	v_mov_b32_e32 v1, v199
	v_readlane_b32 s3, v254, 41
	s_and_b64 vcc, exec, s[2:3]
	v_readfirstlane_b32 s2, v1
	s_cbranch_vccnz .LBB0_869
	v_lshlrev_b32_e32 v4, 4, v1
	v_add_u32_e32 v2, 0x2000, v4
	v_ashrrev_i32_e32 v0, 31, v2
	v_lshrrev_b32_e32 v0, 22, v0
	v_add_u32_e32 v0, v2, v0
	v_ashrrev_i32_e32 v0, 10, v0
	v_mul_i32_i24_e32 v3, 0x400, v0
	v_sub_u32_e32 v2, v2, v3
	v_lshrrev_b32_e32 v3, 4, v2
	v_bitop3_b32 v3, v3, v2, 32 bitop3:0x6c
	v_ashrrev_i32_e32 v2, 31, v3
	v_lshrrev_b32_e32 v2, 26, v2
	v_add_u32_e32 v5, v3, v2
	v_lshlrev_b32_e32 v6, 3, v0
	v_ashrrev_i32_e32 v2, 6, v5
	v_and_b32_e32 v6, -16, v6
	v_add_u32_e32 v6, v2, v6
	v_and_b32_e32 v7, 3, v2
	s_mov_b32 s4, 0x1fffe0
	v_lshrrev_b32_e32 v8, 2, v6
	v_lshlrev_b32_e32 v9, 1, v6
	v_and_b32_e32 v5, 0xc0, v5
	v_and_or_b32 v7, v6, s4, v7
	v_and_b32_e32 v8, 4, v8
	v_and_b32_e32 v9, 24, v9
	v_sub_u32_e32 v3, v3, v5
	v_mov_b32_e32 v12, 1
	v_or3_b32 v7, v7, v8, v9
	v_lshlrev_b32_e32 v8, 5, v0
	v_ashrrev_i16_sdwa v3, v12, sext(v3) dst_sel:DWORD dst_unused:UNUSED_PAD src0_sel:DWORD src1_sel:BYTE_0
	v_and_b32_e32 v8, 32, v8
	v_bfe_i32 v3, v3, 0, 16
	v_add_lshl_u32 v5, v8, v3, 1
	v_lshl_add_u32 v144, v7, 11, v5
	v_lshl_add_u32 v146, v6, 11, v5
	v_bfe_i32 v5, v1, 27, 1
	v_lshrrev_b32_e32 v5, 22, v5
	v_add_u32_e32 v5, v4, v5
	v_and_b32_e32 v5, 0xfffffc00, v5
	v_sub_u32_e32 v4, v4, v5
	v_lshrrev_b32_e32 v5, 4, v4
	v_bitop3_b32 v6, v5, v4, 32 bitop3:0x6c
	v_ashrrev_i32_e32 v5, 31, v1
	v_lshrrev_b32_e32 v5, 26, v5
	v_ashrrev_i32_e32 v4, 31, v6
	v_add_u32_e32 v5, v1, v5
	v_lshrrev_b32_e32 v4, 26, v4
	v_ashrrev_i32_e32 v5, 6, v5
	v_add_u32_e32 v7, v6, v4
	v_lshlrev_b32_e32 v8, 3, v5
	v_ashrrev_i32_e32 v4, 6, v7
	v_and_b32_e32 v8, -16, v8
	v_add_u32_e32 v8, v4, v8
	v_and_b32_e32 v9, 3, v4
	v_lshrrev_b32_e32 v10, 2, v8
	v_lshlrev_b32_e32 v11, 1, v8
	v_and_b32_e32 v7, 0xc0, v7
	v_and_or_b32 v9, v8, s4, v9
	v_and_b32_e32 v10, 4, v10
	v_and_b32_e32 v11, 24, v11
	v_sub_u32_e32 v6, v6, v7
	s_ashr_i32 s3, s2, 6
	v_or3_b32 v9, v9, v10, v11
	v_lshlrev_b32_e32 v10, 5, v5
	v_ashrrev_i16_sdwa v6, v12, sext(v6) dst_sel:DWORD dst_unused:UNUSED_PAD src0_sel:DWORD src1_sel:BYTE_0
	s_lshl_b32 s26, s3, 10
	v_and_b32_e32 v10, 32, v10
	v_bfe_i32 v6, v6, 0, 16
	v_add_lshl_u32 v7, v10, v6, 1
	s_add_i32 s27, s26, 0
	v_readlane_b32 s4, v250, 57
	v_lshl_add_u32 v152, v9, 11, v7
	s_add_i32 m0, s27, 0x10000
	v_readlane_b32 s5, v250, 58
	v_lshl_add_u32 v148, v8, 11, v7
	s_add_i32 s28, s27, 0x2000
	s_add_i32 s29, s27, 0x4000
	s_add_i32 s35, s27, 0x6000
	s_ashr_i32 s6, s2, 8
	global_load_lds_dwordx4 v152, s[4:5]
	s_add_i32 m0, s27, 0x12000
	s_nop 0
	global_load_lds_dwordx4 v144, s[4:5]
	v_readlane_b32 s4, v250, 51
	s_add_i32 m0, s27, 0x14000
	v_readlane_b32 s5, v250, 52
	s_nop 4
	global_load_lds_dwordx4 v152, s[4:5]
	s_add_i32 m0, s27, 0x16000
	s_cmp_eq_u32 s6, 1
	global_load_lds_dwordx4 v144, s[4:5]
	v_readlane_b32 s4, v250, 53
	s_mov_b32 m0, s27
	v_readlane_b32 s5, v250, 54
	s_nop 4
	global_load_lds_dwordx4 v148, s[4:5]
	s_mov_b32 m0, s28
	s_nop 0
	global_load_lds_dwordx4 v146, s[4:5]
	v_readlane_b32 s4, v250, 55
	s_mov_b32 m0, s29
	v_readlane_b32 s5, v250, 56
	s_nop 4
	global_load_lds_dwordx4 v148, s[4:5]
	s_mov_b32 m0, s35
	s_nop 0
	global_load_lds_dwordx4 v146, s[4:5]
	s_cselect_b64 s[4:5], -1, 0
	s_cmp_lg_u32 s6, 1
	s_cbranch_scc1 .LBB0_856
	s_barrier

; #define PG8_STAGE(bufoff, gbase, voff) do { _Pragma("unroll") for (int _i = 0; _i < 2; ++_i) \
;         __builtin_amdgcn_global_load_lds((const unsigned*)((const char*)(gbase) + (voff)[_i]), (LAS unsigned*)(lds + (bufoff) + ldsw + _i * 8192), 16, 0, 0); } while (0)
; #define PG8_WAIT_V(n) asm volatile("s_waitcnt vmcnt(" #n ")" ::: "memory")
; #define PG8_BAR __builtin_amdgcn_s_barrier()
; __device__ __forceinline__ void grid_sync(cg::grid_group& grid) {
;     asm volatile("s_waitcnt vmcnt(0) lgkmcnt(0)" ::: "memory"); grid.sync();
;     __builtin_amdgcn_fence(__ATOMIC_ACQUIRE, "agent"); asm volatile("s_waitcnt vmcnt(0)" ::: "memory"); }
; template <class Epi>
; __device__ __forceinline__ void gemm_phase(LAS unsigned char* lds, const Gemm g, const StaticOrder& S, const Epi& E, const int tid) {
;     ...
;     for (int i = 0; i < 2; ++i) { int R, C; stage_rc(tid * 16 + i * 8192, R, C); const int Rb = Epi::PERM ? ((R & ~31) + perm32(R & 31)) : R;
;         voffA[i] = (unsigned)(R * lda + C) * 2u; voffB[i] = (unsigned)(Rb * K + C) * 2u; }
;     const size_t kstep = (size_t)(BK * 2);
;     const size_t hstepA = (size_t)HALF * lda * 2, hstepB = (size_t)HALF * K * 2;
;     const size_t tstepA = 2 * hstepA, tstepB = 2 * hstepB;
;     const unsigned ldsw = (unsigned)wid * 1024u;
;     const int aoff = lds_byte(wr * 64 + fr, fq * 8), boff = lds_byte(wc * 32 + fr, fq * 8);
;     ...
;     Unit cur, nxt; int ui = 0;
;     if (!S.next(0, cur)) return;
;     f32x4 acc[2][2][4][2];
; #pragma unroll
;     for (int a = 0; a < 2; ++a)
; #pragma unroll
;         for (int b = 0; b < 2; ++b)
; #pragma unroll
;             for (int m = 0; m < 4; ++m)
; #pragma unroll
;                 for (int n = 0; n < 2; ++n) acc[a][b][m][n] = (f32x4){0.f, 0.f, 0.f, 0.f};
;     h16x8 At[4][2], B0[2][2], B1[2][2];
;     const char* cA = (const char*)g.A + (size_t)cur.pm * tstepA; const char* cB = (const char*)g.Bt + (size_t)cur.pn * tstepB;
;     PG8_STAGE(PG8_SB(0, 0), cB, voffB); PG8_STAGE(PG8_SB(0, 1), cB + hstepB, voffB); PG8_STAGE(PG8_SA(0, 0), cA, voffA); PG8_STAGE(PG8_SA(0, 1), cA + hstepA, voffA);
;     if (wr == 1) PG8_BAR;
;     PG8_WAIT_V(2); PG8_BAR;
;     PG8_STAGE(PG8_SB(1, 0), cB + kstep, voffB); PG8_STAGE(PG8_SA(1, 0), cA + kstep, voffA); PG8_STAGE(PG8_SB(1, 1), cB + hstepB + kstep, voffB);
;     PG8_WAIT_V(6); PG8_BAR;
.LBB0_914:
.LBB0_915:
	s_or_b64 exec, exec, s[2:3]
	s_barrier
	s_waitcnt vmcnt(0)
	buffer_inv sc1
	s_waitcnt vmcnt(0)
	v_readlane_b32 s2, v254, 42
	v_mov_b32_e32 v1, v199
	v_readlane_b32 s3, v254, 43
	s_and_b64 vcc, exec, s[2:3]
	v_readfirstlane_b32 s2, v1
	s_cbranch_vccnz .LBB0_955
	v_lshlrev_b32_e32 v5, 4, v1
	v_add_u32_e32 v2, 0x2000, v5
	v_ashrrev_i32_e32 v0, 31, v2
	v_lshrrev_b32_e32 v0, 22, v0
	v_add_u32_e32 v0, v2, v0
	v_ashrrev_i32_e32 v0, 10, v0
	v_mul_i32_i24_e32 v3, 0x400, v0
	v_sub_u32_e32 v2, v2, v3
	v_lshrrev_b32_e32 v3, 4, v2
	v_bitop3_b32 v4, v3, v2, 32 bitop3:0x6c
	v_ashrrev_i32_e32 v2, 31, v4
	v_lshrrev_b32_e32 v2, 26, v2
	v_add_u32_e32 v6, v4, v2
	v_ashrrev_i32_e32 v2, 6, v6
	v_and_b32_e32 v6, 0xc0, v6
	v_sub_u32_e32 v4, v4, v6
	v_bfe_i32 v6, v1, 27, 1
	v_lshrrev_b32_e32 v6, 22, v6
	v_add_u32_e32 v6, v5, v6
	v_and_b32_e32 v6, 0xfffffc00, v6
	v_lshlrev_b32_e32 v3, 3, v0
	v_sub_u32_e32 v5, v5, v6
	v_and_b32_e32 v3, 0xfffff0, v3
	v_lshrrev_b32_e32 v6, 4, v5
	v_add_u32_e32 v3, v2, v3
	v_bitop3_b32 v8, v6, v5, 32 bitop3:0x6c
	v_ashrrev_i32_e32 v6, 31, v1
	v_mul_lo_u32 v7, v3, s72
	v_lshlrev_b32_e32 v3, 5, v0
	v_mov_b32_e32 v11, 1
	v_lshrrev_b32_e32 v6, 26, v6
	v_and_b32_e32 v3, 32, v3
	v_ashrrev_i16_sdwa v4, v11, sext(v4) dst_sel:DWORD dst_unused:UNUSED_PAD src0_sel:DWORD src1_sel:BYTE_0
	v_ashrrev_i32_e32 v5, 31, v8
	v_add_u32_e32 v6, v1, v6
	v_or_b32_e32 v7, v7, v3
	v_bfe_i32 v4, v4, 0, 16
	v_lshrrev_b32_e32 v5, 26, v5
	v_ashrrev_i32_e32 v6, 6, v6
	v_add_lshl_u32 v170, v7, v4, 1
	v_add_u32_e32 v9, v8, v5
	v_lshlrev_b32_e32 v7, 3, v6
	v_ashrrev_i32_e32 v5, 6, v9
	v_and_b32_e32 v7, 0xfffff0, v7
	v_add_u32_e32 v7, v5, v7
	v_and_b32_e32 v9, 0xc0, v9
	s_ashr_i32 s3, s2, 6
	v_mul_lo_u32 v10, v7, s72
	v_lshlrev_b32_e32 v7, 5, v6
	v_sub_u32_e32 v8, v8, v9
	s_lshl_b32 s24, s3, 10
	v_and_b32_e32 v7, 32, v7
	v_ashrrev_i16_sdwa v8, v11, sext(v8) dst_sel:DWORD dst_unused:UNUSED_PAD src0_sel:DWORD src1_sel:BYTE_0
	v_or_b32_e32 v10, v10, v7
	v_bfe_i32 v8, v8, 0, 16
	s_add_i32 s25, s24, 0
	v_readlane_b32 s4, v252, 44
	v_add_lshl_u32 v152, v10, v8, 1
	s_add_i32 m0, s25, 0x10000
	v_readlane_b32 s5, v252, 45
	s_add_i32 s26, s25, 0x2000
	s_add_i32 s27, s25, 0x4000
	s_add_i32 s28, s25, 0x6000
	s_ashr_i32 s6, s2, 8
	s_nop 0
	global_load_lds_dwordx4 v152, s[4:5]
	s_add_i32 m0, s25, 0x12000
	s_nop 0
	global_load_lds_dwordx4 v170, s[4:5]
	v_readlane_b32 s4, v252, 42
	s_add_i32 m0, s25, 0x14000
	v_readlane_b32 s5, v252, 43
	s_nop 4
	global_load_lds_dwordx4 v152, s[4:5]
	s_add_i32 m0, s25, 0x16000
	s_cmp_eq_u32 s6, 1
	global_load_lds_dwordx4 v170, s[4:5]
	v_readlane_b32 s4, v251, 2
	s_mov_b32 m0, s25
	v_readlane_b32 s5, v251, 3
	s_nop 4
	global_load_lds_dwordx4 v152, s[4:5]
	s_mov_b32 m0, s26
	s_nop 0
	global_load_lds_dwordx4 v170, s[4:5]
	v_readlane_b32 s4, v251, 4
	s_mov_b32 m0, s27
	v_readlane_b32 s5, v251, 5
	s_nop 4
	global_load_lds_dwordx4 v152, s[4:5]
	s_mov_b32 m0, s28
	s_nop 0
	global_load_lds_dwordx4 v170, s[4:5]
	s_cselect_b64 s[4:5], -1, 0
	s_cmp_lg_u32 s6, 1
	s_cbranch_scc1 .LBB0_918
	s_barrier

; #define PG8_STAGE(bufoff, gbase, voff) do { _Pragma("unroll") for (int _i = 0; _i < 2; ++_i) \
;         __builtin_amdgcn_global_load_lds((const unsigned*)((const char*)(gbase) + (voff)[_i]), (LAS unsigned*)(lds + (bufoff) + ldsw + _i * 8192), 16, 0, 0); } while (0)
; #define PG8_WAIT_V(n) asm volatile("s_waitcnt vmcnt(" #n ")" ::: "memory")
; #define PG8_BAR __builtin_amdgcn_s_barrier()
; __device__ __forceinline__ void grid_sync(cg::grid_group& grid) {
;     asm volatile("s_waitcnt vmcnt(0) lgkmcnt(0)" ::: "memory"); grid.sync();
;     __builtin_amdgcn_fence(__ATOMIC_ACQUIRE, "agent"); asm volatile("s_waitcnt vmcnt(0)" ::: "memory"); }
; template <class Epi>
; __device__ __forceinline__ void gemm_phase(LAS unsigned char* lds, const Gemm g, const StaticOrder& S, const Epi& E, const int tid) {
;     ...
;     for (int i = 0; i < 2; ++i) { int R, C; stage_rc(tid * 16 + i * 8192, R, C); const int Rb = Epi::PERM ? ((R & ~31) + perm32(R & 31)) : R;
;         voffA[i] = (unsigned)(R * lda + C) * 2u; voffB[i] = (unsigned)(Rb * K + C) * 2u; }
;     const size_t kstep = (size_t)(BK * 2);
;     const size_t hstepA = (size_t)HALF * lda * 2, hstepB = (size_t)HALF * K * 2;
;     const size_t tstepA = 2 * hstepA, tstepB = 2 * hstepB;
;     const unsigned ldsw = (unsigned)wid * 1024u;
;     const int aoff = lds_byte(wr * 64 + fr, fq * 8), boff = lds_byte(wc * 32 + fr, fq * 8);
;     ...
;     Unit cur, nxt; int ui = 0;
;     if (!S.next(0, cur)) return;
;     f32x4 acc[2][2][4][2];
; #pragma unroll
;     for (int a = 0; a < 2; ++a)
; #pragma unroll
;         for (int b = 0; b < 2; ++b)
; #pragma unroll
;             for (int m = 0; m < 4; ++m)
; #pragma unroll
;                 for (int n = 0; n < 2; ++n) acc[a][b][m][n] = (f32x4){0.f, 0.f, 0.f, 0.f};
;     h16x8 At[4][2], B0[2][2], B1[2][2];
;     const char* cA = (const char*)g.A + (size_t)cur.pm * tstepA; const char* cB = (const char*)g.Bt + (size_t)cur.pn * tstepB;
;     PG8_STAGE(PG8_SB(0, 0), cB, voffB); PG8_STAGE(PG8_SB(0, 1), cB + hstepB, voffB); PG8_STAGE(PG8_SA(0, 0), cA, voffA); PG8_STAGE(PG8_SA(0, 1), cA + hstepA, voffA);
;     if (wr == 1) PG8_BAR;
;     PG8_WAIT_V(2); PG8_BAR;
;     PG8_STAGE(PG8_SB(1, 0), cB + kstep, voffB); PG8_STAGE(PG8_SA(1, 0), cA + kstep, voffA); PG8_STAGE(PG8_SB(1, 1), cB + hstepB + kstep, voffB);
;     PG8_WAIT_V(6); PG8_BAR;
.LBB0_967:
.LBB0_968:
	s_or_b64 exec, exec, s[2:3]
	s_barrier
	s_waitcnt vmcnt(0)
	buffer_inv sc1
	s_waitcnt vmcnt(0)
	v_readlane_b32 s2, v254, 42
	v_mov_b32_e32 v0, v199
	v_readlane_b32 s3, v254, 43
	s_movk_i32 s6, 0x100
	s_and_b64 vcc, exec, s[2:3]
	v_readfirstlane_b32 s8, v0
	s_cbranch_vccnz .LBB0_994
	v_lshlrev_b32_e32 v4, 4, v0
	v_add_u32_e32 v1, 0x2000, v4
	v_ashrrev_i32_e32 v2, 31, v1
	v_lshrrev_b32_e32 v2, 22, v2
	v_add_u32_e32 v2, v1, v2
	v_ashrrev_i32_e32 v2, 10, v2
	v_mul_i32_i24_e32 v3, 0x400, v2
	v_sub_u32_e32 v1, v1, v3
	v_lshrrev_b32_e32 v3, 4, v1
	v_bitop3_b32 v3, v3, v1, 32 bitop3:0x6c
	v_ashrrev_i32_e32 v1, 31, v3
	v_lshrrev_b32_e32 v1, 26, v1
	v_add_u32_e32 v5, v3, v1
	v_lshlrev_b32_e32 v6, 3, v2
	v_ashrrev_i32_e32 v1, 6, v5
	v_and_b32_e32 v6, -16, v6
	v_add_u32_e32 v6, v1, v6
	v_and_b32_e32 v1, 3, v1
	s_mov_b32 s2, 0x7fffffe0
	v_lshrrev_b32_e32 v7, 2, v6
	v_lshlrev_b32_e32 v8, 1, v6
	v_and_or_b32 v1, v6, s2, v1
	v_and_b32_e32 v7, 4, v7
	v_and_b32_e32 v8, 24, v8
	v_or3_b32 v1, v1, v7, v8
	v_mul_lo_u32 v7, v1, s6
	v_lshlrev_b32_e32 v1, 5, v2
	v_and_b32_e32 v2, 0xc0, v5
	v_sub_u32_e32 v2, v3, v2
	v_mov_b32_e32 v11, 1
	v_ashrrev_i16_sdwa v2, v11, sext(v2) dst_sel:DWORD dst_unused:UNUSED_PAD src0_sel:DWORD src1_sel:BYTE_0
	v_and_b32_e32 v1, 32, v1
	v_bfe_i32 v2, v2, 0, 16
	v_add_u32_e32 v5, v1, v2
	v_mul_lo_u32 v3, v6, s6
	v_add_lshl_u32 v128, v7, v5, 1
	v_add_lshl_u32 v130, v5, v3, 1
	v_bfe_i32 v5, v0, 27, 1
	v_lshrrev_b32_e32 v5, 22, v5
	v_add_u32_e32 v5, v4, v5
	v_and_b32_e32 v5, 0xfffffc00, v5
	v_sub_u32_e32 v4, v4, v5
	v_lshrrev_b32_e32 v5, 4, v4
	v_ashrrev_i32_e32 v7, 31, v0
	v_bitop3_b32 v5, v5, v4, 32 bitop3:0x6c
	v_lshrrev_b32_e32 v7, 26, v7
	v_ashrrev_i32_e32 v4, 31, v5
	v_add_u32_e32 v7, v0, v7
	v_lshrrev_b32_e32 v4, 26, v4
	v_ashrrev_i32_e32 v7, 6, v7
	v_add_u32_e32 v6, v5, v4
	v_lshlrev_b32_e32 v8, 3, v7
	s_ashr_i32 s7, s6, 31
	v_ashrrev_i32_e32 v4, 6, v6
	v_and_b32_e32 v8, -16, v8
	v_readlane_b32 s16, v252, 8
	s_lshl_b64 s[10:11], s[6:7], 9
	v_add_u32_e32 v8, v4, v8
	v_and_b32_e32 v4, 3, v4
	v_readlane_b32 s17, v252, 9
	v_and_or_b32 v4, v8, s2, v4
	s_mul_i32 s2, s10, s17
	s_mul_hi_u32 s3, s10, s16
	s_add_i32 s12, s3, s2
	s_lshr_b64 s[2:3], s[6:7], 23
	s_mul_i32 s3, s2, s16
	s_mul_i32 s13, s10, s16
	v_readlane_b32 s16, v252, 10
	v_lshrrev_b32_e32 v9, 2, v8
	v_lshlrev_b32_e32 v10, 1, v8
	v_readlane_b32 s17, v252, 11
	v_and_b32_e32 v9, 4, v9
	v_and_b32_e32 v10, 24, v10
	v_and_b32_e32 v6, 0xc0, v6
	s_add_i32 s12, s12, s3
	s_mul_i32 s3, s10, s17
	s_mul_hi_u32 s15, s10, s16
	s_ashr_i32 s9, s8, 6
	v_or3_b32 v4, v4, v9, v10
	v_sub_u32_e32 v5, v5, v6
	s_add_i32 s3, s15, s3
	s_mul_i32 s2, s2, s16
	s_ashr_i32 s14, s8, 8
	s_lshl_b64 s[4:5], s[6:7], 8
	s_lshl_b32 s24, s9, 10
	v_mul_lo_u32 v9, v4, s6
	v_lshlrev_b32_e32 v4, 5, v7
	v_ashrrev_i16_sdwa v5, v11, sext(v5) dst_sel:DWORD dst_unused:UNUSED_PAD src0_sel:DWORD src1_sel:BYTE_0
	s_add_i32 s3, s3, s2
	s_mul_i32 s2, s10, s16
	v_readlane_b32 s16, v249, 8
	v_and_b32_e32 v4, 32, v4
	v_bfe_i32 v5, v5, 0, 16
	v_readlane_b32 s17, v249, 9
	s_add_u32 s22, s16, s2
	v_add_u32_e32 v7, v4, v5
	s_addc_u32 s23, s17, s3
	s_add_i32 s25, s24, 0
	v_add_lshl_u32 v152, v9, v7, 1
	s_add_i32 m0, s25, 0x10000
	v_readlane_b32 s15, v250, 17
	global_load_lds_dwordx4 v152, s[22:23]
	s_add_i32 m0, s25, 0x12000
	s_add_u32 s2, s22, s4
	global_load_lds_dwordx4 v128, s[22:23]
	s_addc_u32 s3, s23, s5
	s_add_i32 m0, s25, 0x14000
	v_mul_lo_u32 v6, v8, s6
	global_load_lds_dwordx4 v152, s[2:3]
	s_add_i32 m0, s25, 0x16000
	s_add_u32 s20, s15, s13
	v_readlane_b32 s13, v250, 18
	s_addc_u32 s21, s13, s12
	s_add_i32 s26, s25, 0x2000
	v_add_lshl_u32 v132, v7, v6, 1
	global_load_lds_dwordx4 v128, s[2:3]
	s_mov_b32 m0, s25
	s_add_u32 s12, s20, s4
	global_load_lds_dwordx4 v132, s[20:21]
	s_mov_b32 m0, s26
	s_addc_u32 s13, s21, s5
	s_add_i32 s27, s25, 0x4000
	global_load_lds_dwordx4 v130, s[20:21]
	s_mov_b32 m0, s27
	s_add_i32 s28, s25, 0x6000
	global_load_lds_dwordx4 v132, s[12:13]
	s_mov_b32 m0, s28
	s_cmp_eq_u32 s14, 1
	global_load_lds_dwordx4 v130, s[12:13]
	s_cselect_b64 s[12:13], -1, 0
	s_cmp_lg_u32 s14, 1
	s_cbranch_scc1 .LBB0_971
	s_barrier

; #define PG8_STAGE(bufoff, gbase, voff) do { _Pragma("unroll") for (int _i = 0; _i < 2; ++_i) \
;         __builtin_amdgcn_global_load_lds((const unsigned*)((const char*)(gbase) + (voff)[_i]), (LAS unsigned*)(lds + (bufoff) + ldsw + _i * 8192), 16, 0, 0); } while (0)
; #define PG8_WAIT_V(n) asm volatile("s_waitcnt vmcnt(" #n ")" ::: "memory")
; #define PG8_BAR __builtin_amdgcn_s_barrier()
; __device__ __forceinline__ void grid_sync(cg::grid_group& grid) {
;     asm volatile("s_waitcnt vmcnt(0) lgkmcnt(0)" ::: "memory"); grid.sync();
;     __builtin_amdgcn_fence(__ATOMIC_ACQUIRE, "agent"); asm volatile("s_waitcnt vmcnt(0)" ::: "memory"); }
; template <class Epi>
; __device__ __forceinline__ void gemm_phase(LAS unsigned char* lds, const Gemm g, const StaticOrder& S, const Epi& E, const int tid) {
;     ...
;     for (int i = 0; i < 2; ++i) { int R, C; stage_rc(tid * 16 + i * 8192, R, C); const int Rb = Epi::PERM ? ((R & ~31) + perm32(R & 31)) : R;
;         voffA[i] = (unsigned)(R * lda + C) * 2u; voffB[i] = (unsigned)(Rb * K + C) * 2u; }
;     const size_t kstep = (size_t)(BK * 2);
;     const size_t hstepA = (size_t)HALF * lda * 2, hstepB = (size_t)HALF * K * 2;
;     const size_t tstepA = 2 * hstepA, tstepB = 2 * hstepB;
;     const unsigned ldsw = (unsigned)wid * 1024u;
;     const int aoff = lds_byte(wr * 64 + fr, fq * 8), boff = lds_byte(wc * 32 + fr, fq * 8);
;     ...
;     Unit cur, nxt; int ui = 0;
;     if (!S.next(0, cur)) return;
;     f32x4 acc[2][2][4][2];
; #pragma unroll
;     for (int a = 0; a < 2; ++a)
; #pragma unroll
;         for (int b = 0; b < 2; ++b)
; #pragma unroll
;             for (int m = 0; m < 4; ++m)
; #pragma unroll
;                 for (int n = 0; n < 2; ++n) acc[a][b][m][n] = (f32x4){0.f, 0.f, 0.f, 0.f};
;     h16x8 At[4][2], B0[2][2], B1[2][2];
;     const char* cA = (const char*)g.A + (size_t)cur.pm * tstepA; const char* cB = (const char*)g.Bt + (size_t)cur.pn * tstepB;
;     PG8_STAGE(PG8_SB(0, 0), cB, voffB); PG8_STAGE(PG8_SB(0, 1), cB + hstepB, voffB); PG8_STAGE(PG8_SA(0, 0), cA, voffA); PG8_STAGE(PG8_SA(0, 1), cA + hstepA, voffA);
;     if (wr == 1) PG8_BAR;
;     PG8_WAIT_V(2); PG8_BAR;
;     PG8_STAGE(PG8_SB(1, 0), cB + kstep, voffB); PG8_STAGE(PG8_SA(1, 0), cA + kstep, voffA); PG8_STAGE(PG8_SB(1, 1), cB + hstepB + kstep, voffB);
;     PG8_WAIT_V(6); PG8_BAR;
.LBB0_1003:
.LBB0_1004:
	s_or_b64 exec, exec, s[2:3]
	s_barrier
	buffer_inv sc1
	s_waitcnt vmcnt(0)
	v_readlane_b32 s2, v254, 42
	v_mov_b32_e32 v1, v199
	v_readlane_b32 s3, v254, 43
	s_and_b64 vcc, exec, s[2:3]
	v_readfirstlane_b32 s2, v1
	s_cbranch_vccnz .LBB0_1040
	v_lshlrev_b32_e32 v5, 4, v1
	v_add_u32_e32 v2, 0x2000, v5
	v_ashrrev_i32_e32 v0, 31, v2
	v_lshrrev_b32_e32 v0, 22, v0
	v_add_u32_e32 v0, v2, v0
	v_ashrrev_i32_e32 v0, 10, v0
	v_lshlrev_b32_e32 v3, 5, v0
	v_and_b32_e32 v4, 32, v3
	v_mul_i32_i24_e32 v3, 0x400, v0
	v_sub_u32_e32 v2, v2, v3
	v_lshrrev_b32_e32 v3, 4, v2
	v_bitop3_b32 v3, v3, v2, 32 bitop3:0x6c
	v_ashrrev_i32_e32 v2, 31, v3
	v_lshrrev_b32_e32 v2, 26, v2
	v_add_u32_e32 v6, v3, v2
	v_ashrrev_i32_e32 v2, 6, v6
	v_and_b32_e32 v6, 0xc0, v6
	v_sub_u32_e32 v3, v3, v6
	v_mov_b32_e32 v9, 1
	v_ashrrev_i16_sdwa v3, v9, sext(v3) dst_sel:DWORD dst_unused:UNUSED_PAD src0_sel:DWORD src1_sel:BYTE_0
	v_lshlrev_b32_e32 v6, 3, v0
	v_bfe_i32 v3, v3, 0, 16
	v_and_b32_e32 v6, 0x1ffff0, v6
	v_add_u32_e32 v4, v4, v3
	v_add_lshl_u32 v6, v2, v6, 11
	v_lshl_add_u32 v128, v4, 1, v6
	v_ashrrev_i32_e32 v4, 31, v1
	v_lshrrev_b32_e32 v4, 26, v4
	v_add_u32_e32 v4, v1, v4
	v_ashrrev_i32_e32 v4, 6, v4
	v_lshlrev_b32_e32 v6, 5, v4
	v_and_b32_e32 v7, 32, v6
	v_bfe_i32 v6, v1, 27, 1
	v_lshrrev_b32_e32 v6, 22, v6
	v_add_u32_e32 v6, v5, v6
	v_and_b32_e32 v6, 0xfffffc00, v6
	v_sub_u32_e32 v5, v5, v6
	v_lshrrev_b32_e32 v6, 4, v5
	v_bitop3_b32 v6, v6, v5, 32 bitop3:0x6c
	v_ashrrev_i32_e32 v5, 31, v6
	v_lshrrev_b32_e32 v5, 26, v5
	v_add_u32_e32 v8, v6, v5
	v_ashrrev_i32_e32 v5, 6, v8
	v_and_b32_e32 v8, 0xc0, v8
	v_sub_u32_e32 v6, v6, v8
	s_ashr_i32 s3, s2, 6
	v_ashrrev_i16_sdwa v6, v9, sext(v6) dst_sel:DWORD dst_unused:UNUSED_PAD src0_sel:DWORD src1_sel:BYTE_0
	v_lshlrev_b32_e32 v8, 3, v4
	s_lshl_b32 s26, s3, 10
	v_bfe_i32 v6, v6, 0, 16
	v_and_b32_e32 v8, 0x1ffff0, v8
	v_add_u32_e32 v7, v7, v6
	v_add_lshl_u32 v8, v5, v8, 11
	s_add_i32 s27, s26, 0
	v_readlane_b32 s4, v252, 56
	v_lshl_add_u32 v152, v7, 1, v8
	s_add_i32 m0, s27, 0x10000
	v_readlane_b32 s5, v252, 57
	s_add_i32 s28, s27, 0x2000
	s_add_i32 s29, s27, 0x4000
	s_add_i32 s35, s27, 0x6000
	s_nop 1
	global_load_lds_dwordx4 v152, s[4:5]
	s_add_i32 m0, s27, 0x12000
	s_nop 0
	global_load_lds_dwordx4 v128, s[4:5]
	v_readlane_b32 s4, v252, 50
	s_add_i32 m0, s27, 0x14000
	v_readlane_b32 s5, v252, 51
	s_nop 4
	global_load_lds_dwordx4 v152, s[4:5]
	s_add_i32 m0, s27, 0x16000
	s_nop 0
	global_load_lds_dwordx4 v128, s[4:5]
	v_readlane_b32 s4, v252, 52
	s_mov_b32 m0, s27
	v_readlane_b32 s5, v252, 53
	s_nop 4
	global_load_lds_dwordx4 v152, s[4:5]
	s_mov_b32 m0, s28
	s_nop 0
	global_load_lds_dwordx4 v128, s[4:5]
	v_readlane_b32 s4, v252, 54
	s_mov_b32 m0, s29
	v_readlane_b32 s5, v252, 55
	s_nop 4
	global_load_lds_dwordx4 v152, s[4:5]
	s_mov_b32 m0, s35
	s_nop 0
	global_load_lds_dwordx4 v128, s[4:5]
	s_ashr_i32 s4, s2, 8
	s_cmp_eq_u32 s4, 1
	s_cselect_b64 s[6:7], -1, 0
	s_cmp_lg_u32 s4, 1
	s_cbranch_scc1 .LBB0_1007
	s_barrier
